# attention prompt loop Q.K^T: 16 K-fragment reads up front, two back-to-back accumulate chains instead of alternating accumulators with single-buffered fragments
# speedup vs baseline: 1.0044x; 1.0044x over previous
.LBB0_458:
	s_and_b32 s73, s70, 1
	s_cmp_lt_u32 s71, 9
	s_cselect_b64 s[80:81], -1, 0
	s_and_b64 s[80:81], s[76:77], s[80:81]
	s_andn2_b64 vcc, exec, s[80:81]
	s_cbranch_vccnz .LBB0_468
	s_lshl_b32 s82, s73, 14
	s_add_i32 s67, s82, 0
	v_add3_u32 v64, s67, v192, v191
	ds_read_b128 v[96:99], v64 offset:32768
	v_add3_u32 v206, s67, v193, v191
	ds_read_b128 v[100:103], v206 offset:32768
	v_add3_u32 v210, s67, v194, v191
	ds_read_b128 v[104:107], v210 offset:32768
	v_add3_u32 v224, s67, v195, v191
	ds_read_b128 v[108:111], v224 offset:32768
	v_add3_u32 v238, s67, v197, v191
	ds_read_b128 v[112:115], v238 offset:32768
	v_add3_u32 v242, s67, v198, v191
	ds_read_b128 v[116:119], v242 offset:32768
	v_add3_u32 v246, s67, v199, v191
	ds_read_b128 v[120:123], v246 offset:32768
	v_add3_u32 v250, s67, v200, v191
	ds_read_b128 v[124:127], v250 offset:32768
	ds_read_b128 v[64:67], v64 offset:40960
	ds_read_b128 v[206:209], v206 offset:40960
	ds_read_b128 v[210:213], v210 offset:40960
	ds_read_b128 v[224:227], v224 offset:40960
	ds_read_b128 v[238:241], v238 offset:40960
	ds_read_b128 v[242:245], v242 offset:40960
	ds_read_b128 v[246:249], v246 offset:40960
	s_mov_b64 s[80:81], -1
	s_waitcnt vmcnt(7) lgkmcnt(14)
	v_mfma_f32_32x32x16_bf16 v[80:95], v[96:99], v[144:147], 0
	ds_read_b128 v[250:253], v250 offset:40960
	s_waitcnt vmcnt(6) lgkmcnt(14)
	v_mfma_f32_32x32x16_bf16 v[80:95], v[100:103], v[148:151], v[80:95]
	s_waitcnt vmcnt(5) lgkmcnt(13)
	v_mfma_f32_32x32x16_bf16 v[80:95], v[104:107], v[152:155], v[80:95]
	s_waitcnt vmcnt(4) lgkmcnt(12)
	v_mfma_f32_32x32x16_bf16 v[80:95], v[108:111], v[156:159], v[80:95]
	s_waitcnt vmcnt(3) lgkmcnt(11)
	v_mfma_f32_32x32x16_bf16 v[80:95], v[112:115], v[160:163], v[80:95]
	s_waitcnt vmcnt(2) lgkmcnt(10)
	v_mfma_f32_32x32x16_bf16 v[80:95], v[116:119], v[164:167], v[80:95]
	s_waitcnt vmcnt(1) lgkmcnt(9)
	v_mfma_f32_32x32x16_bf16 v[80:95], v[120:123], v[168:171], v[80:95]
	s_waitcnt vmcnt(0) lgkmcnt(8)
	v_mfma_f32_32x32x16_bf16 v[80:95], v[124:127], v[172:175], v[80:95]
	s_waitcnt lgkmcnt(7)
	v_mfma_f32_32x32x16_bf16 v[64:79], v[64:67], v[144:147], 0
	s_waitcnt lgkmcnt(6)
	v_mfma_f32_32x32x16_bf16 v[64:79], v[206:209], v[148:151], v[64:79]
	s_waitcnt lgkmcnt(5)
	v_mfma_f32_32x32x16_bf16 v[64:79], v[210:213], v[152:155], v[64:79]
	s_waitcnt lgkmcnt(4)
	v_mfma_f32_32x32x16_bf16 v[64:79], v[224:227], v[156:159], v[64:79]
	s_waitcnt lgkmcnt(3)
	v_mfma_f32_32x32x16_bf16 v[64:79], v[238:241], v[160:163], v[64:79]
	s_waitcnt lgkmcnt(2)
	v_mfma_f32_32x32x16_bf16 v[64:79], v[242:245], v[164:167], v[64:79]
	s_waitcnt lgkmcnt(1)
	v_mfma_f32_32x32x16_bf16 v[64:79], v[246:249], v[168:171], v[64:79]
	s_waitcnt lgkmcnt(0)
	v_mfma_f32_32x32x16_bf16 v[64:79], v[250:253], v[172:175], v[64:79]
	s_cmp_lt_u32 s71, 3
	s_cbranch_scc0 .LBB0_461
	v_min_i32_e32 v96, 0x80, v202
	v_min_i32_e32 v97, 0xa0, v202
	s_add_i32 s67, 0, 0x10800
	v_min_i32_e32 v98, 0x81, v202
	v_min_i32_e32 v99, 0xa1, v202
	v_min_i32_e32 v100, 0x82, v202
	v_min_i32_e32 v101, 0xa2, v202
	v_min_i32_e32 v102, 0x83, v202
	v_min_i32_e32 v103, 0xa3, v202
	v_lshl_add_u32 v96, v96, 2, s67
	v_lshl_add_u32 v97, v97, 2, s67
	v_lshl_add_u32 v98, v98, 2, s67
	v_lshl_add_u32 v99, v99, 2, s67
	v_lshl_add_u32 v100, v100, 2, s67
	v_lshl_add_u32 v101, v101, 2, s67
	v_lshl_add_u32 v102, v102, 2, s67
	v_lshl_add_u32 v103, v103, 2, s67
	ds_read_b32 v96, v96 offset:512
	ds_read_b32 v112, v97 offset:384
	ds_read_b32 v97, v98 offset:508
	ds_read_b32 v113, v99 offset:380
	ds_read_b32 v98, v100 offset:504
	ds_read_b32 v114, v101 offset:376
	ds_read_b32 v99, v102 offset:500
	ds_read_b32 v115, v103 offset:372
	v_min_i32_e32 v100, 0x88, v202
	v_min_i32_e32 v101, 0xa8, v202
	v_min_i32_e32 v102, 0x89, v202
	v_min_i32_e32 v103, 0xa9, v202
	v_min_i32_e32 v104, 0x8a, v202
	v_min_i32_e32 v105, 0xaa, v202
	v_min_i32_e32 v106, 0x8b, v202
	v_min_i32_e32 v107, 0xab, v202
	v_lshl_add_u32 v100, v100, 2, s67
	v_lshl_add_u32 v101, v101, 2, s67
	v_lshl_add_u32 v102, v102, 2, s67
	v_lshl_add_u32 v103, v103, 2, s67
	v_lshl_add_u32 v104, v104, 2, s67
	v_lshl_add_u32 v105, v105, 2, s67
	v_lshl_add_u32 v106, v106, 2, s67
	v_lshl_add_u32 v107, v107, 2, s67
	ds_read_b32 v100, v100 offset:480
	ds_read_b32 v116, v101 offset:352
	ds_read_b32 v101, v102 offset:476
	ds_read_b32 v117, v103 offset:348
	ds_read_b32 v102, v104 offset:472
	ds_read_b32 v118, v105 offset:344
	ds_read_b32 v103, v106 offset:468
	ds_read_b32 v119, v107 offset:340
	v_min_i32_e32 v104, 0x90, v202
	v_min_i32_e32 v105, 0xb0, v202
	v_min_i32_e32 v106, 0x91, v202
	v_min_i32_e32 v107, 0xb1, v202
	v_min_i32_e32 v111, 0xb3, v202
	v_lshl_add_u32 v104, v104, 2, s67
	v_lshl_add_u32 v105, v105, 2, s67
	v_lshl_add_u32 v106, v106, 2, s67
	v_lshl_add_u32 v107, v107, 2, s67
	v_min_i32_e32 v108, 0x92, v202
	v_min_i32_e32 v109, 0xb2, v202
	v_min_i32_e32 v110, 0x93, v202
	v_lshl_add_u32 v111, v111, 2, s67
	v_lshl_add_u32 v108, v108, 2, s67
	v_lshl_add_u32 v109, v109, 2, s67
	v_lshl_add_u32 v110, v110, 2, s67
	ds_read_b32 v104, v104 offset:448
	ds_read_b32 v120, v105 offset:320
	ds_read_b32 v105, v106 offset:444
	ds_read_b32 v121, v107 offset:316
	ds_read_b32 v106, v108 offset:440
	ds_read_b32 v122, v109 offset:312
	ds_read_b32 v107, v110 offset:436
	ds_read_b32 v123, v111 offset:308
	v_min_i32_e32 v111, 0xb9, v202
	v_min_i32_e32 v110, 0x99, v202
	v_lshl_add_u32 v205, v111, 2, s67
	v_min_i32_e32 v111, 0xba, v202
	v_min_i32_e32 v108, 0x98, v202
	v_min_i32_e32 v109, 0xb8, v202
	v_lshl_add_u32 v125, v110, 2, s67
	v_min_i32_e32 v110, 0x9a, v202
	v_lshl_add_u32 v126, v111, 2, s67
	v_min_i32_e32 v111, 0x9b, v202
	v_min_i32_e32 v124, 0xbb, v202
	v_lshl_add_u32 v108, v108, 2, s67
	v_lshl_add_u32 v109, v109, 2, s67
	v_lshl_add_u32 v110, v110, 2, s67
	v_lshl_add_u32 v111, v111, 2, s67
	v_lshl_add_u32 v127, v124, 2, s67
	ds_read_b32 v108, v108 offset:416
	ds_read_b32 v124, v109 offset:288
	ds_read_b32 v110, v110 offset:408
	ds_read_b32 v111, v111 offset:404
	ds_read_b32 v109, v125 offset:412
	ds_read_b32 v127, v127 offset:276
	ds_read_b32 v126, v126 offset:280
	ds_read_b32 v125, v205 offset:284
	s_waitcnt lgkmcnt(4)
	v_pk_fma_f32 v[110:111], v[94:95], s[42:43], v[110:111] op_sel_hi:[1,0,1]
	s_waitcnt lgkmcnt(3)
	v_pk_fma_f32 v[108:109], v[92:93], s[42:43], v[108:109] op_sel_hi:[1,0,1]
	v_pk_fma_f32 v[106:107], v[90:91], s[42:43], v[106:107] op_sel_hi:[1,0,1]
	v_pk_fma_f32 v[104:105], v[88:89], s[42:43], v[104:105] op_sel_hi:[1,0,1]
	v_pk_fma_f32 v[102:103], v[86:87], s[42:43], v[102:103] op_sel_hi:[1,0,1]
	v_pk_fma_f32 v[100:101], v[84:85], s[42:43], v[100:101] op_sel_hi:[1,0,1]
	v_pk_fma_f32 v[98:99], v[82:83], s[42:43], v[98:99] op_sel_hi:[1,0,1]
	v_pk_fma_f32 v[96:97], v[80:81], s[42:43], v[96:97] op_sel_hi:[1,0,1]
	s_waitcnt lgkmcnt(1)
	v_pk_fma_f32 v[126:127], v[78:79], s[42:43], v[126:127] op_sel_hi:[1,0,1]
	s_waitcnt lgkmcnt(0)
	v_pk_fma_f32 v[124:125], v[76:77], s[42:43], v[124:125] op_sel_hi:[1,0,1]
	v_pk_fma_f32 v[122:123], v[74:75], s[42:43], v[122:123] op_sel_hi:[1,0,1]
	v_pk_fma_f32 v[120:121], v[72:73], s[42:43], v[120:121] op_sel_hi:[1,0,1]
	v_pk_fma_f32 v[118:119], v[70:71], s[42:43], v[118:119] op_sel_hi:[1,0,1]
	v_pk_fma_f32 v[116:117], v[68:69], s[42:43], v[116:117] op_sel_hi:[1,0,1]
	v_pk_fma_f32 v[114:115], v[66:67], s[42:43], v[114:115] op_sel_hi:[1,0,1]
	v_pk_fma_f32 v[112:113], v[64:65], s[42:43], v[112:113] op_sel_hi:[1,0,1]
	s_mov_b64 s[80:81], 0
